# v025 + w_in: relaxed first waits of a new unit count 16 epilogue stores (vmcnt 24) when the wave took the bf16 store path
# baseline (speedup 1.0000x reference)
.LBB0_251:
	s_cmp_eq_u32 s30, 0
	s_cselect_b64 s[34:35], -1, 0
	s_and_b64 s[34:35], s[0:1], s[34:35]
	v_cndmask_b32_e64 v2, 0, 1, s[34:35]
	s_nop 0
	v_readfirstlane_b32 s34, v2
	s_and_b32 s34, s34, 1
	ds_read_b128 v[26:29], v232
	ds_read_b128 v[30:33], v232 offset:1024
	ds_read_b128 v[18:21], v232 offset:2048
	ds_read_b128 v[22:25], v232 offset:3072
	ds_read_b128 v[10:13], v233
	ds_read_b128 v[14:17], v233 offset:1024
	ds_read_b128 v[2:5], v233 offset:2048
	ds_read_b128 v[6:9], v233 offset:3072
	v_lshl_add_u64 v[222:223], v[220:221], 0, s[30:31]
	s_add_i32 m0, s49, 0xc000
	ds_read_b128 v[58:61], v234
	ds_read_b128 v[62:65], v234 offset:1024
	ds_read_b128 v[50:53], v234 offset:2048
	ds_read_b128 v[54:57], v234 offset:3072
	ds_read_b128 v[42:45], v234 offset:4096
	ds_read_b128 v[46:49], v234 offset:5120
	ds_read_b128 v[34:37], v234 offset:6144
	ds_read_b128 v[38:41], v234 offset:7168
	global_load_lds_dwordx4 v[222:223], off
	v_lshl_add_u64 v[222:223], v[218:219], 0, s[30:31]
	s_add_i32 m0, s49, 0xe000
	s_cmp_lg_u32 s34, 0
	global_load_lds_dwordx4 v[222:223], off
	s_cselect_b64 s[38:39], -1, 0
	s_cmp_eq_u32 s34, 0
	s_cbranch_scc1 .LBB0_256
	s_cmp_eq_u32 s99, 0
	s_cbranch_scc1 .Lrx_0
	s_waitcnt vmcnt(24)
	s_branch .Lry_0
.Lrx_0:
	s_waitcnt vmcnt(16)
.Lry_0:
	s_cbranch_execnz .LBB0_254

.LBB0_254:
	s_add_u32 s34, s6, s30
	s_addc_u32 s35, s7, s31
	s_add_u32 s34, s34, 0x100
	s_addc_u32 s35, s35, 0
	s_add_u32 s81, s78, s30
	s_addc_u32 s82, s79, s31
	s_waitcnt lgkmcnt(0)
	s_cmpk_eq_i32 s30, 0x700
	s_cselect_b32 s37, s27, s35
	s_cselect_b32 s36, s26, s34
	s_cselect_b32 s35, s5, s82
	s_cselect_b32 s34, s25, s81
	s_barrier
	s_setprio 1
	s_waitcnt lgkmcnt(0)
	v_mfma_f32_16x16x128_f8f6f4 v[190:193], v[26:33], v[58:65], v[190:193]
	v_mfma_f32_16x16x128_f8f6f4 v[186:189], v[18:25], v[58:65], v[186:189]
	v_mfma_f32_16x16x128_f8f6f4 v[174:177], v[26:33], v[50:57], v[174:177]
	v_mfma_f32_16x16x128_f8f6f4 v[170:173], v[18:25], v[50:57], v[170:173]
	v_mfma_f32_16x16x128_f8f6f4 v[158:161], v[26:33], v[42:49], v[158:161]
	v_mfma_f32_16x16x128_f8f6f4 v[154:157], v[18:25], v[42:49], v[154:157]
	v_mfma_f32_16x16x128_f8f6f4 v[142:145], v[26:33], v[34:41], v[142:145]
	v_mfma_f32_16x16x128_f8f6f4 v[138:141], v[18:25], v[34:41], v[138:141]
	s_setprio 0
	s_setprio 1
	v_mfma_f32_16x16x128_f8f6f4 v[182:185], v[10:17], v[58:65], v[182:185]
	v_mfma_f32_16x16x128_f8f6f4 v[178:181], v[2:9], v[58:65], v[178:181]
	v_mfma_f32_16x16x128_f8f6f4 v[166:169], v[10:17], v[50:57], v[166:169]
	v_mfma_f32_16x16x128_f8f6f4 v[162:165], v[2:9], v[50:57], v[162:165]
	v_mfma_f32_16x16x128_f8f6f4 v[150:153], v[10:17], v[42:49], v[150:153]
	v_mfma_f32_16x16x128_f8f6f4 v[146:149], v[2:9], v[42:49], v[146:149]
	v_mfma_f32_16x16x128_f8f6f4 v[134:137], v[10:17], v[34:41], v[134:137]
	v_mfma_f32_16x16x128_f8f6f4 v[130:133], v[2:9], v[34:41], v[130:133]
	s_setprio 0
	s_barrier
	s_mov_b32 m0, s45
	v_lshl_add_u64 v[222:223], s[34:35], 0, v[196:197]
	s_add_u32 s82, s34, 0x40000
	ds_read_b128 v[58:61], v234 offset:16384
	ds_read_b128 v[62:65], v234 offset:17408
	ds_read_b128 v[50:53], v234 offset:18432
	ds_read_b128 v[54:57], v234 offset:19456
	ds_read_b128 v[42:45], v234 offset:20480
	ds_read_b128 v[46:49], v234 offset:21504
	ds_read_b128 v[34:37], v234 offset:22528
	ds_read_b128 v[38:41], v234 offset:23552
	global_load_lds_dwordx4 v[222:223], off
	v_lshl_add_u64 v[224:225], s[34:35], 0, v[200:201]
	s_mov_b32 m0, s46
	s_addc_u32 s83, s35, 0
	global_load_lds_dwordx4 v[224:225], off
	v_lshl_add_u64 v[226:227], s[82:83], 0, v[196:197]
	s_mov_b32 m0, s47
	v_lshl_add_u64 v[228:229], s[36:37], 0, v[198:199]
	global_load_lds_dwordx4 v[226:227], off
	v_lshl_add_u64 v[226:227], s[82:83], 0, v[200:201]
	s_mov_b32 m0, s48
	s_andn2_b64 vcc, exec, s[38:39]
	global_load_lds_dwordx4 v[226:227], off
	v_lshl_add_u64 v[226:227], s[36:37], 0, v[194:195]
	s_mov_b32 m0, s49
	s_nop 0
	global_load_lds_dwordx4 v[226:227], off
	s_mov_b32 m0, s50
	s_nop 0
	global_load_lds_dwordx4 v[228:229], off
	s_cbranch_vccnz .LBB0_257
	s_cmp_eq_u32 s99, 0
	s_cbranch_scc1 .Lrx_1
	s_waitcnt vmcnt(24)
	s_branch .Lry_1

.Lry_1:
	s_cbranch_execnz .LBB0_250
	s_branch .LBB0_249

.LBB0_260:
	v_lshl_or_b32 v4, s4, 8, v231
	v_cmp_gt_i32_e32 vcc, s67, v4
	v_add_u32_e32 v14, 0xffffcfc0, v4
	v_add_u32_e32 v2, 0xffffcdc0, v4
	v_cndmask_b32_e64 v3, 0, 1, vcc
	v_cmp_lt_i32_e32 vcc, s65, v4
	v_add_u32_e32 v13, 0xfffff1c0, v4
	v_cmp_gt_u32_e64 s[0:1], s70, v14
	v_cndmask_b32_e64 v5, 0, 1, vcc
	v_cmp_lt_i32_e32 vcc, s66, v4
	v_lshl_add_u32 v12, s77, 8, v1
	v_cmp_gt_u32_e64 s[4:5], s69, v13
	v_cndmask_b32_e32 v3, v5, v3, vcc
	v_and_b32_e32 v3, 1, v3
	v_cmp_eq_u32_e32 vcc, 1, v3
	s_or_b64 s[0:1], vcc, s[0:1]
	v_cmp_gt_u32_e64 s[6:7], s68, v2
	s_nor_b64 s[0:1], s[4:5], s[0:1]
	v_ashrrev_i32_e32 v5, 31, v4
	v_cndmask_b32_e64 v2, v236, v237, s[6:7]
	v_or_b32_e32 v11, 16, v12
	v_or_b32_e32 v10, 32, v12
	v_or_b32_e32 v9, 48, v12
	v_add_u32_e32 v8, 0x80, v12
	v_add_u32_e32 v7, 0x90, v12
	v_add_u32_e32 v6, 0xa0, v12
	v_add_u32_e32 v3, 0xb0, v12
	s_nop 15
	s_nop 15
	s_mov_b32 s99, 0
	s_and_saveexec_b64 s[30:31], s[0:1]
	s_xor_b64 s[0:1], exec, s[30:31]
	s_cbranch_execz .LBB0_263
	s_mov_b32 s99, 1
	v_pk_mul_f32 v[14:15], v[2:3], v[192:193] op_sel_hi:[0,1]
	v_pk_mul_f32 v[16:17], v[2:3], v[190:191] op_sel_hi:[0,1]
	v_pk_mul_f32 v[18:19], v[2:3], v[188:189] op_sel_hi:[0,1]
	v_pk_mul_f32 v[20:21], v[2:3], v[186:187] op_sel_hi:[0,1]
	v_cvt_pk_bf16_f32 v13, v16, v17
	v_cvt_pk_bf16_f32 v22, v14, v15
	v_cvt_pk_bf16_f32 v23, v20, v21
	v_cvt_pk_bf16_f32 v24, v18, v19
	v_pk_mul_f32 v[16:17], v[2:3], v[184:185] op_sel_hi:[0,1]
	v_pk_mul_f32 v[14:15], v[2:3], v[182:183] op_sel_hi:[0,1]
	v_pk_mul_f32 v[18:19], v[2:3], v[180:181] op_sel_hi:[0,1]
	v_pk_mul_f32 v[20:21], v[2:3], v[178:179] op_sel_hi:[0,1]
	v_cvt_pk_bf16_f32 v14, v14, v15
	v_cvt_pk_bf16_f32 v15, v16, v17
	v_cvt_pk_bf16_f32 v16, v20, v21
	v_cvt_pk_bf16_f32 v17, v18, v19
	v_mov_b32_e32 v18, v13
	v_lshl_add_u64 v[4:5], v[4:5], 1, v[208:209]
	v_mov_b32_e32 v19, v22
	v_mov_b32_dpp v18, v14 row_ror:8 row_mask:0xf bank_mask:0xc
	v_mov_b32_dpp v14, v13 row_ror:8 row_mask:0xf bank_mask:0x3
	v_ashrrev_i32_e32 v13, 31, v12
	v_sub_co_u32_e32 v12, vcc, v12, v204
	v_mov_b32_dpp v19, v15 row_ror:8 row_mask:0xf bank_mask:0xc
	v_mov_b32_dpp v15, v22 row_ror:8 row_mask:0xf bank_mask:0x3
	v_mov_b32_e32 v20, v23
	v_mov_b32_e32 v21, v24
	v_subbrev_co_u32_e32 v22, vcc, 0, v13, vcc
	v_mad_u64_u32 v[12:13], s[30:31], v12, s71, v[4:5]
	v_mov_b32_dpp v20, v16 row_ror:8 row_mask:0xf bank_mask:0xc
	v_mov_b32_dpp v21, v17 row_ror:8 row_mask:0xf bank_mask:0xc
	v_mad_i32_i24 v13, v22, s71, v13
	global_store_dwordx4 v[12:13], v[18:21], off
	v_add_co_u32_e32 v12, vcc, s63, v12
	v_mov_b32_dpp v16, v23 row_ror:8 row_mask:0xf bank_mask:0x3
	v_mov_b32_dpp v17, v24 row_ror:8 row_mask:0xf bank_mask:0x3
	v_addc_co_u32_e32 v13, vcc, 0, v13, vcc
	global_store_dwordx4 v[12:13], v[14:17], off
	v_pk_mul_f32 v[12:13], v[2:3], v[176:177] op_sel_hi:[0,1]
	v_pk_mul_f32 v[18:19], v[2:3], v[170:171] op_sel_hi:[0,1]
	v_pk_mul_f32 v[14:15], v[2:3], v[174:175] op_sel_hi:[0,1]
	v_pk_mul_f32 v[16:17], v[2:3], v[172:173] op_sel_hi:[0,1]
	v_cvt_pk_bf16_f32 v20, v14, v15
	v_cvt_pk_bf16_f32 v21, v12, v13
	v_cvt_pk_bf16_f32 v22, v18, v19
	v_cvt_pk_bf16_f32 v23, v16, v17
	v_pk_mul_f32 v[14:15], v[2:3], v[168:169] op_sel_hi:[0,1]
	v_pk_mul_f32 v[12:13], v[2:3], v[166:167] op_sel_hi:[0,1]
	v_pk_mul_f32 v[16:17], v[2:3], v[164:165] op_sel_hi:[0,1]
	v_pk_mul_f32 v[18:19], v[2:3], v[162:163] op_sel_hi:[0,1]
	v_cvt_pk_bf16_f32 v12, v12, v13
	v_cvt_pk_bf16_f32 v13, v14, v15
	v_cvt_pk_bf16_f32 v14, v18, v19
	v_cvt_pk_bf16_f32 v15, v16, v17
	v_mov_b32_e32 v16, v20
	v_mov_b32_e32 v17, v21
	v_mov_b32_e32 v18, v22
	v_mov_b32_dpp v16, v12 row_ror:8 row_mask:0xf bank_mask:0xc
	v_mov_b32_dpp v12, v20 row_ror:8 row_mask:0xf bank_mask:0x3
	v_ashrrev_i32_e32 v20, 31, v11
	v_sub_co_u32_e32 v11, vcc, v11, v204
	v_mov_b32_dpp v17, v13 row_ror:8 row_mask:0xf bank_mask:0xc
	v_mov_b32_dpp v13, v21 row_ror:8 row_mask:0xf bank_mask:0x3
	v_mov_b32_dpp v18, v14 row_ror:8 row_mask:0xf bank_mask:0xc
	v_mov_b32_dpp v14, v22 row_ror:8 row_mask:0xf bank_mask:0x3
	v_mov_b32_e32 v19, v23
	v_subbrev_co_u32_e32 v22, vcc, 0, v20, vcc
	v_mad_u64_u32 v[20:21], s[30:31], v11, s71, v[4:5]
	v_mov_b32_dpp v19, v15 row_ror:8 row_mask:0xf bank_mask:0xc
	v_mad_i32_i24 v21, v22, s71, v21
	global_store_dwordx4 v[20:21], v[16:19], off
	v_mov_b32_dpp v15, v23 row_ror:8 row_mask:0xf bank_mask:0x3
	s_nop 0
	v_add_co_u32_e32 v16, vcc, s63, v20
	v_pk_mul_f32 v[18:19], v[2:3], v[154:155] op_sel_hi:[0,1]
	s_nop 0
	v_addc_co_u32_e32 v17, vcc, 0, v21, vcc
	global_store_dwordx4 v[16:17], v[12:15], off
	v_pk_mul_f32 v[16:17], v[2:3], v[156:157] op_sel_hi:[0,1]
	s_nop 0
	v_pk_mul_f32 v[12:13], v[2:3], v[160:161] op_sel_hi:[0,1]
	v_pk_mul_f32 v[14:15], v[2:3], v[158:159] op_sel_hi:[0,1]
	v_cvt_pk_bf16_f32 v11, v14, v15
	v_cvt_pk_bf16_f32 v20, v12, v13
	v_cvt_pk_bf16_f32 v21, v18, v19
	v_cvt_pk_bf16_f32 v22, v16, v17
	v_pk_mul_f32 v[14:15], v[2:3], v[152:153] op_sel_hi:[0,1]
	v_pk_mul_f32 v[12:13], v[2:3], v[150:151] op_sel_hi:[0,1]
	v_pk_mul_f32 v[16:17], v[2:3], v[148:149] op_sel_hi:[0,1]
	v_pk_mul_f32 v[18:19], v[2:3], v[146:147] op_sel_hi:[0,1]
	v_cvt_pk_bf16_f32 v12, v12, v13
	v_cvt_pk_bf16_f32 v13, v14, v15
	v_cvt_pk_bf16_f32 v14, v18, v19
	v_cvt_pk_bf16_f32 v15, v16, v17
	v_mov_b32_e32 v16, v11
	v_mov_b32_e32 v17, v20
	v_mov_b32_e32 v18, v21
	v_mov_b32_dpp v16, v12 row_ror:8 row_mask:0xf bank_mask:0xc
	v_mov_b32_dpp v12, v11 row_ror:8 row_mask:0xf bank_mask:0x3
	v_ashrrev_i32_e32 v11, 31, v10
	v_sub_co_u32_e32 v10, vcc, v10, v204
	v_mov_b32_dpp v17, v13 row_ror:8 row_mask:0xf bank_mask:0xc
	v_mov_b32_dpp v13, v20 row_ror:8 row_mask:0xf bank_mask:0x3
	v_mov_b32_e32 v19, v22
	v_subbrev_co_u32_e32 v20, vcc, 0, v11, vcc
	v_mad_u64_u32 v[10:11], s[30:31], v10, s71, v[4:5]
	v_mov_b32_dpp v18, v14 row_ror:8 row_mask:0xf bank_mask:0xc
	v_mov_b32_dpp v19, v15 row_ror:8 row_mask:0xf bank_mask:0xc
	v_mad_i32_i24 v11, v20, s71, v11
	global_store_dwordx4 v[10:11], v[16:19], off
	v_add_co_u32_e32 v10, vcc, s63, v10
	v_mov_b32_dpp v14, v21 row_ror:8 row_mask:0xf bank_mask:0x3
	v_mov_b32_dpp v15, v22 row_ror:8 row_mask:0xf bank_mask:0x3
	v_addc_co_u32_e32 v11, vcc, 0, v11, vcc
	global_store_dwordx4 v[10:11], v[12:15], off
	v_pk_mul_f32 v[10:11], v[2:3], v[144:145] op_sel_hi:[0,1]
	v_pk_mul_f32 v[16:17], v[2:3], v[138:139] op_sel_hi:[0,1]
	v_pk_mul_f32 v[12:13], v[2:3], v[142:143] op_sel_hi:[0,1]
	v_pk_mul_f32 v[14:15], v[2:3], v[140:141] op_sel_hi:[0,1]
	v_cvt_pk_bf16_f32 v18, v12, v13
	v_cvt_pk_bf16_f32 v19, v10, v11
	v_cvt_pk_bf16_f32 v20, v16, v17
	v_cvt_pk_bf16_f32 v21, v14, v15
	v_pk_mul_f32 v[12:13], v[2:3], v[136:137] op_sel_hi:[0,1]
	v_pk_mul_f32 v[10:11], v[2:3], v[134:135] op_sel_hi:[0,1]
	v_pk_mul_f32 v[14:15], v[2:3], v[132:133] op_sel_hi:[0,1]
	v_pk_mul_f32 v[16:17], v[2:3], v[130:131] op_sel_hi:[0,1]
	v_cvt_pk_bf16_f32 v10, v10, v11
	v_cvt_pk_bf16_f32 v11, v12, v13
	v_cvt_pk_bf16_f32 v12, v16, v17
	v_cvt_pk_bf16_f32 v13, v14, v15
	v_mov_b32_e32 v14, v18
	v_mov_b32_e32 v15, v19
	v_mov_b32_e32 v16, v20
	v_mov_b32_dpp v14, v10 row_ror:8 row_mask:0xf bank_mask:0xc
	v_mov_b32_dpp v10, v18 row_ror:8 row_mask:0xf bank_mask:0x3
	v_ashrrev_i32_e32 v18, 31, v9
	v_sub_co_u32_e32 v9, vcc, v9, v204
	v_mov_b32_dpp v15, v11 row_ror:8 row_mask:0xf bank_mask:0xc
	v_mov_b32_dpp v11, v19 row_ror:8 row_mask:0xf bank_mask:0x3
	v_mov_b32_dpp v16, v12 row_ror:8 row_mask:0xf bank_mask:0xc
	v_mov_b32_dpp v12, v20 row_ror:8 row_mask:0xf bank_mask:0x3
	v_mov_b32_e32 v17, v21
	v_subbrev_co_u32_e32 v20, vcc, 0, v18, vcc
	v_mad_u64_u32 v[18:19], s[30:31], v9, s71, v[4:5]
	v_mov_b32_dpp v17, v13 row_ror:8 row_mask:0xf bank_mask:0xc
	v_mad_i32_i24 v19, v20, s71, v19
	global_store_dwordx4 v[18:19], v[14:17], off
	v_mov_b32_dpp v13, v21 row_ror:8 row_mask:0xf bank_mask:0x3
	s_nop 0
	v_add_co_u32_e32 v14, vcc, s63, v18
	v_pk_mul_f32 v[16:17], v[2:3], v[122:123] op_sel_hi:[0,1]
	s_nop 0
	v_addc_co_u32_e32 v15, vcc, 0, v19, vcc
	global_store_dwordx4 v[14:15], v[10:13], off
	v_pk_mul_f32 v[14:15], v[2:3], v[124:125] op_sel_hi:[0,1]
	s_nop 0
	v_pk_mul_f32 v[10:11], v[2:3], v[128:129] op_sel_hi:[0,1]
	v_pk_mul_f32 v[12:13], v[2:3], v[126:127] op_sel_hi:[0,1]
	v_cvt_pk_bf16_f32 v9, v12, v13
	v_cvt_pk_bf16_f32 v18, v10, v11
	v_cvt_pk_bf16_f32 v19, v16, v17
	v_cvt_pk_bf16_f32 v20, v14, v15
	v_pk_mul_f32 v[12:13], v[2:3], v[120:121] op_sel_hi:[0,1]
	v_pk_mul_f32 v[10:11], v[2:3], v[118:119] op_sel_hi:[0,1]
	v_pk_mul_f32 v[14:15], v[2:3], v[116:117] op_sel_hi:[0,1]
	v_pk_mul_f32 v[16:17], v[2:3], v[114:115] op_sel_hi:[0,1]
	v_cvt_pk_bf16_f32 v10, v10, v11
	v_cvt_pk_bf16_f32 v11, v12, v13
	v_cvt_pk_bf16_f32 v12, v16, v17
	v_cvt_pk_bf16_f32 v13, v14, v15
	v_mov_b32_e32 v14, v9
	v_mov_b32_e32 v15, v18
	v_mov_b32_e32 v16, v19
	v_mov_b32_dpp v14, v10 row_ror:8 row_mask:0xf bank_mask:0xc
	v_mov_b32_dpp v10, v9 row_ror:8 row_mask:0xf bank_mask:0x3
	v_ashrrev_i32_e32 v9, 31, v8
	v_sub_co_u32_e32 v8, vcc, v8, v204
	v_mov_b32_dpp v15, v11 row_ror:8 row_mask:0xf bank_mask:0xc
	v_mov_b32_dpp v11, v18 row_ror:8 row_mask:0xf bank_mask:0x3
	v_mov_b32_e32 v17, v20
	v_subbrev_co_u32_e32 v18, vcc, 0, v9, vcc
	v_mad_u64_u32 v[8:9], s[30:31], v8, s71, v[4:5]
	v_mov_b32_dpp v16, v12 row_ror:8 row_mask:0xf bank_mask:0xc
	v_mov_b32_dpp v17, v13 row_ror:8 row_mask:0xf bank_mask:0xc
	v_mad_i32_i24 v9, v18, s71, v9
	global_store_dwordx4 v[8:9], v[14:17], off
	v_add_co_u32_e32 v8, vcc, s63, v8
	v_mov_b32_dpp v12, v19 row_ror:8 row_mask:0xf bank_mask:0x3
	v_mov_b32_dpp v13, v20 row_ror:8 row_mask:0xf bank_mask:0x3
	v_addc_co_u32_e32 v9, vcc, 0, v9, vcc
	global_store_dwordx4 v[8:9], v[10:13], off
	v_pk_mul_f32 v[8:9], v[2:3], v[112:113] op_sel_hi:[0,1]
	v_pk_mul_f32 v[14:15], v[2:3], v[106:107] op_sel_hi:[0,1]
	v_pk_mul_f32 v[10:11], v[2:3], v[110:111] op_sel_hi:[0,1]
	v_pk_mul_f32 v[12:13], v[2:3], v[108:109] op_sel_hi:[0,1]
	v_cvt_pk_bf16_f32 v16, v10, v11
	v_cvt_pk_bf16_f32 v17, v8, v9
	v_cvt_pk_bf16_f32 v18, v14, v15
	v_cvt_pk_bf16_f32 v19, v12, v13
	v_pk_mul_f32 v[10:11], v[2:3], v[104:105] op_sel_hi:[0,1]
	v_pk_mul_f32 v[8:9], v[2:3], v[102:103] op_sel_hi:[0,1]
	v_pk_mul_f32 v[12:13], v[2:3], v[100:101] op_sel_hi:[0,1]
	v_pk_mul_f32 v[14:15], v[2:3], v[98:99] op_sel_hi:[0,1]
	v_cvt_pk_bf16_f32 v8, v8, v9
	v_cvt_pk_bf16_f32 v9, v10, v11
	v_cvt_pk_bf16_f32 v10, v14, v15
	v_cvt_pk_bf16_f32 v11, v12, v13
	v_mov_b32_e32 v12, v16
	v_mov_b32_e32 v13, v17
	v_mov_b32_e32 v14, v18
	v_mov_b32_dpp v12, v8 row_ror:8 row_mask:0xf bank_mask:0xc
	v_mov_b32_dpp v8, v16 row_ror:8 row_mask:0xf bank_mask:0x3
	v_ashrrev_i32_e32 v16, 31, v7
	v_sub_co_u32_e32 v7, vcc, v7, v204
	v_mov_b32_dpp v13, v9 row_ror:8 row_mask:0xf bank_mask:0xc
	v_mov_b32_dpp v9, v17 row_ror:8 row_mask:0xf bank_mask:0x3
	v_mov_b32_dpp v14, v10 row_ror:8 row_mask:0xf bank_mask:0xc
	v_mov_b32_dpp v10, v18 row_ror:8 row_mask:0xf bank_mask:0x3
	v_mov_b32_e32 v15, v19
	v_subbrev_co_u32_e32 v18, vcc, 0, v16, vcc
	v_mad_u64_u32 v[16:17], s[30:31], v7, s71, v[4:5]
	v_mov_b32_dpp v15, v11 row_ror:8 row_mask:0xf bank_mask:0xc
	v_mad_i32_i24 v17, v18, s71, v17
	global_store_dwordx4 v[16:17], v[12:15], off
	v_mov_b32_dpp v11, v19 row_ror:8 row_mask:0xf bank_mask:0x3
	s_nop 0
	v_add_co_u32_e32 v12, vcc, s63, v16
	v_pk_mul_f32 v[14:15], v[2:3], v[90:91] op_sel_hi:[0,1]
	s_nop 0
	v_addc_co_u32_e32 v13, vcc, 0, v17, vcc
	global_store_dwordx4 v[12:13], v[8:11], off
	v_pk_mul_f32 v[12:13], v[2:3], v[92:93] op_sel_hi:[0,1]
	s_nop 0
	v_pk_mul_f32 v[8:9], v[2:3], v[96:97] op_sel_hi:[0,1]
	v_pk_mul_f32 v[10:11], v[2:3], v[94:95] op_sel_hi:[0,1]
	v_cvt_pk_bf16_f32 v7, v10, v11
	v_cvt_pk_bf16_f32 v16, v8, v9
	v_cvt_pk_bf16_f32 v17, v14, v15
	v_cvt_pk_bf16_f32 v18, v12, v13
	v_pk_mul_f32 v[10:11], v[2:3], v[88:89] op_sel_hi:[0,1]
	v_pk_mul_f32 v[8:9], v[2:3], v[86:87] op_sel_hi:[0,1]
	v_pk_mul_f32 v[12:13], v[2:3], v[84:85] op_sel_hi:[0,1]
	v_pk_mul_f32 v[14:15], v[2:3], v[82:83] op_sel_hi:[0,1]
	v_cvt_pk_bf16_f32 v8, v8, v9
	v_cvt_pk_bf16_f32 v9, v10, v11
	v_cvt_pk_bf16_f32 v10, v14, v15
	v_cvt_pk_bf16_f32 v11, v12, v13
	v_mov_b32_e32 v12, v7
	v_mov_b32_e32 v13, v16
	v_mov_b32_e32 v14, v17
	v_mov_b32_dpp v12, v8 row_ror:8 row_mask:0xf bank_mask:0xc
	v_mov_b32_dpp v8, v7 row_ror:8 row_mask:0xf bank_mask:0x3
	v_ashrrev_i32_e32 v7, 31, v6
	v_sub_co_u32_e32 v6, vcc, v6, v204
	v_mov_b32_dpp v13, v9 row_ror:8 row_mask:0xf bank_mask:0xc
	v_mov_b32_dpp v9, v16 row_ror:8 row_mask:0xf bank_mask:0x3
	v_mov_b32_e32 v15, v18
	v_subbrev_co_u32_e32 v16, vcc, 0, v7, vcc
	v_mad_u64_u32 v[6:7], s[30:31], v6, s71, v[4:5]
	v_mov_b32_dpp v14, v10 row_ror:8 row_mask:0xf bank_mask:0xc
	v_mov_b32_dpp v15, v11 row_ror:8 row_mask:0xf bank_mask:0xc
	v_mad_i32_i24 v7, v16, s71, v7
	global_store_dwordx4 v[6:7], v[12:15], off
	v_add_co_u32_e32 v6, vcc, s63, v6
	v_mov_b32_dpp v10, v17 row_ror:8 row_mask:0xf bank_mask:0x3
	v_mov_b32_dpp v11, v18 row_ror:8 row_mask:0xf bank_mask:0x3
	v_addc_co_u32_e32 v7, vcc, 0, v7, vcc
	global_store_dwordx4 v[6:7], v[8:11], off
	v_pk_mul_f32 v[6:7], v[2:3], v[80:81] op_sel_hi:[0,1]
	v_pk_mul_f32 v[12:13], v[2:3], v[74:75] op_sel_hi:[0,1]
	v_pk_mul_f32 v[8:9], v[2:3], v[78:79] op_sel_hi:[0,1]
	v_pk_mul_f32 v[10:11], v[2:3], v[76:77] op_sel_hi:[0,1]
	v_cvt_pk_bf16_f32 v14, v8, v9
	v_cvt_pk_bf16_f32 v15, v6, v7
	v_cvt_pk_bf16_f32 v16, v12, v13
	v_cvt_pk_bf16_f32 v17, v10, v11
	v_pk_mul_f32 v[8:9], v[2:3], v[72:73] op_sel_hi:[0,1]
	v_pk_mul_f32 v[6:7], v[2:3], v[70:71] op_sel_hi:[0,1]
	v_pk_mul_f32 v[10:11], v[2:3], v[68:69] op_sel_hi:[0,1]
	v_pk_mul_f32 v[12:13], v[2:3], v[66:67] op_sel_hi:[0,1]
	v_cvt_pk_bf16_f32 v6, v6, v7
	v_cvt_pk_bf16_f32 v7, v8, v9
	v_cvt_pk_bf16_f32 v8, v12, v13
	v_cvt_pk_bf16_f32 v9, v10, v11
	v_mov_b32_e32 v10, v14
	v_ashrrev_i32_e32 v2, 31, v3
	v_sub_co_u32_e32 v3, vcc, v3, v204
	v_mov_b32_dpp v10, v6 row_ror:8 row_mask:0xf bank_mask:0xc
	v_mov_b32_dpp v6, v14 row_ror:8 row_mask:0xf bank_mask:0x3
	v_mov_b32_e32 v11, v15
	v_mov_b32_e32 v12, v16
	v_mov_b32_e32 v13, v17
	v_subbrev_co_u32_e32 v14, vcc, 0, v2, vcc
	v_mad_u64_u32 v[2:3], s[30:31], v3, s71, v[4:5]
	v_mov_b32_dpp v11, v7 row_ror:8 row_mask:0xf bank_mask:0xc
	v_mov_b32_dpp v12, v8 row_ror:8 row_mask:0xf bank_mask:0xc
	v_mov_b32_dpp v13, v9 row_ror:8 row_mask:0xf bank_mask:0xc
	v_mad_i32_i24 v3, v14, s71, v3
	global_store_dwordx4 v[2:3], v[10:13], off
	v_add_co_u32_e32 v2, vcc, 0x53000, v2
	v_mov_b32_dpp v7, v15 row_ror:8 row_mask:0xf bank_mask:0x3
	v_mov_b32_dpp v8, v16 row_ror:8 row_mask:0xf bank_mask:0x3
	v_mov_b32_dpp v9, v17 row_ror:8 row_mask:0xf bank_mask:0x3
	v_addc_co_u32_e32 v3, vcc, 0, v3, vcc
	global_store_dwordx4 v[2:3], v[6:9], off
	s_andn2_saveexec_b64 s[30:31], s[0:1]
	s_cbranch_execnz .LBB0_264

	.amdhsa_kernel _Z10fwd_kernel4Args
		.amdhsa_group_segment_fixed_size 0
		.amdhsa_private_segment_fixed_size 0
		.amdhsa_kernarg_size 448
		.amdhsa_user_sgpr_count 2
		.amdhsa_user_sgpr_dispatch_ptr 0
		.amdhsa_user_sgpr_queue_ptr 0
		.amdhsa_user_sgpr_kernarg_segment_ptr 1
		.amdhsa_user_sgpr_dispatch_id 0
		.amdhsa_user_sgpr_kernarg_preload_length 0
		.amdhsa_user_sgpr_kernarg_preload_offset 0
		.amdhsa_user_sgpr_private_segment_size 0
		.amdhsa_uses_dynamic_stack 0
		.amdhsa_enable_private_segment 0
		.amdhsa_system_sgpr_workgroup_id_x 1
		.amdhsa_system_sgpr_workgroup_id_y 0
		.amdhsa_system_sgpr_workgroup_id_z 0
		.amdhsa_system_sgpr_workgroup_info 0
		.amdhsa_system_vgpr_workitem_id 0
		.amdhsa_next_free_vgpr 253
		.amdhsa_next_free_sgpr 100
		.amdhsa_accum_offset 256
		.amdhsa_reserve_vcc 1
		.amdhsa_float_round_mode_32 0
		.amdhsa_float_round_mode_16_64 0
		.amdhsa_float_denorm_mode_32 3
		.amdhsa_float_denorm_mode_16_64 3
		.amdhsa_dx10_clamp 1
		.amdhsa_ieee_mode 1
		.amdhsa_fp16_overflow 0
		.amdhsa_tg_split 0
		.amdhsa_exception_fp_ieee_invalid_op 0
		.amdhsa_exception_fp_denorm_src 0
		.amdhsa_exception_fp_ieee_div_zero 0
		.amdhsa_exception_fp_ieee_overflow 0
		.amdhsa_exception_fp_ieee_underflow 0
		.amdhsa_exception_fp_ieee_inexact 0
		.amdhsa_exception_int_div_zero 0
	.end_amdhsa_kernel

amdhsa.kernels:
  - .agpr_count:     0
    .args:
      - .offset:         0
        .size:           192
        .value_kind:     by_value
      - .offset:         192
        .size:           4
        .value_kind:     hidden_block_count_x
      - .offset:         196
        .size:           4
        .value_kind:     hidden_block_count_y
      - .offset:         200
        .size:           4
        .value_kind:     hidden_block_count_z
      - .offset:         204
        .size:           2
        .value_kind:     hidden_group_size_x
      - .offset:         206
        .size:           2
        .value_kind:     hidden_group_size_y
      - .offset:         208
        .size:           2
        .value_kind:     hidden_group_size_z
      - .offset:         210
        .size:           2
        .value_kind:     hidden_remainder_x
      - .offset:         212
        .size:           2
        .value_kind:     hidden_remainder_y
      - .offset:         214
        .size:           2
        .value_kind:     hidden_remainder_z
      - .offset:         232
        .size:           8
        .value_kind:     hidden_global_offset_x
      - .offset:         240
        .size:           8
        .value_kind:     hidden_global_offset_y
      - .offset:         248
        .size:           8
        .value_kind:     hidden_global_offset_z
      - .offset:         256
        .size:           2
        .value_kind:     hidden_grid_dims
      - .offset:         312
        .size:           4
        .value_kind:     hidden_dynamic_lds_size
    .group_segment_fixed_size: 0
    .kernarg_segment_align: 8
    .kernarg_segment_size: 448
    .language:       OpenCL C
    .language_version:
      - 2
      - 0
    .max_flat_workgroup_size: 512
    .name:           _Z10fwd_kernel4Args
    .private_segment_fixed_size: 0
    .sgpr_count:     106
    .sgpr_spill_count: 54
    .symbol:         _Z10fwd_kernel4Args.kd
    .uniform_work_group_size: 1
    .uses_dynamic_stack: false
    .vgpr_count:     253
    .vgpr_spill_count: 0
    .wavefront_size: 64
